# K-loops: 4th-segment DMA addresses via offset:128 (six VALU adds per iteration removed) with one pad so that no MFMA crosses a 64-byte line; loop heads at 20 / 16 / 12 mod 64
# baseline (speedup 1.0000x reference)
; #define PG8_STAGE(bufoff, gbase, voff) do { _Pragma("unroll") for (int _i = 0; _i < 2; ++_i) \
;         __builtin_amdgcn_global_load_lds((const unsigned*)((const char*)(gbase) + (voff)[_i]), (LAS unsigned*)(lds + (bufoff) + ldsw + _i * 8192), 16, 0, 0); } while (0)
; #define PG8_LDA(dst, b, h) do { _Pragma("unroll") for (int m = 0; m < 4; ++m) _Pragma("unroll") for (int k = 0; k < 2; ++k) dst[m][k] = *(const LAS bf16x8*)(lds + PG8_SA(b, h) + aoff + m * 2048 + k * 1024); } while (0)
; #define PG8_LDB(dst, b, h) do { _Pragma("unroll") for (int n = 0; n < 2; ++n) _Pragma("unroll") for (int k = 0; k < 2; ++k) dst[n][k] = *(const LAS bf16x8*)(lds + PG8_SB(b, h) + boff + n * 2048 + k * 1024); } while (0)
; #define PG8_MMA(ai, bj, At, Bt) do { __builtin_amdgcn_s_setprio(1); _Pragma("unroll") for (int m = 0; m < 4; ++m) _Pragma("unroll") for (int n = 0; n < 2; ++n) _Pragma("unroll") for (int k = 0; k < 2; ++k) \
;         acc[ai][bj][m][n] = __builtin_amdgcn_mfma_f32_16x16x32_bf16(Bt[n][k], At[m][k], acc[ai][bj][m][n], 0, 0, 0); __builtin_amdgcn_s_setprio(0); } while (0)
; #define PG8_WAIT_V(n) asm volatile("s_waitcnt vmcnt(" #n ")" ::: "memory")
; #define PG8_WAIT_L(n) asm volatile("s_waitcnt lgkmcnt(" #n ")" ::: "memory")
; #define PG8_BAR __builtin_amdgcn_s_barrier()
; #define PG8_SCHED __builtin_amdgcn_sched_barrier(0)
;     ...
;             const bool last = (t == nt - 2);
;             const char* a1 = cA + (size_t)(t + 1) * kstep;
;             const char* a2 = last ? nA : cA + (size_t)(t + 2) * kstep; const char* b2 = last ? nB : cB + (size_t)(t + 2) * kstep;
;             const char* a3 = a2 + kstep; const char* b3 = b2 + kstep;
;             PG8_LDB(B0, 0, 0); PG8_LDB(B1, 0, 1); PG8_SCHED; PG8_LDA(At, 0, 0); PG8_STAGE(PG8_SA(1, 1), a1 + hstepA, voffA);
;             PG8_WAIT_V(8); PG8_WAIT_L(0); PG8_BAR; PG8_MMA(0, 0, At, B0); PG8_MMA(0, 1, At, B1); PG8_BAR; PG8_SCHED;
;             PG8_LDA(At, 0, 1); PG8_STAGE(PG8_SB(0, 0), b2, voffB); PG8_STAGE(PG8_SB(0, 1), b2 + hstepB, voffB); PG8_STAGE(PG8_SA(0, 0), a2, voffA);
;             PG8_WAIT_V(8); PG8_WAIT_L(0); PG8_BAR; PG8_MMA(1, 0, At, B0); PG8_MMA(1, 1, At, B1); PG8_BAR; PG8_SCHED;
.LBB0_159:
	s_add_i32 s38, s8, 2
	s_add_u32 s26, s12, s0
	s_addc_u32 s9, s13, s1
	s_add_i32 s27, 0, 0x10000
	s_cmp_eq_u32 s63, s8
	s_cselect_b32 s9, s18, s9
	s_cselect_b32 s8, s19, s26
	s_cselect_b64 vcc, -1, 0
	s_add_i32 s26, 0, 0x14000
	v_lshl_add_u64 v[150:151], v[188:189], 0, s[0:1]
	v_add_u32_e32 v146, s27, v226
	v_add_u32_e32 v162, s26, v226
	ds_read_b128 v[134:137], v146
	ds_read_b128 v[138:141], v146 offset:1024
	ds_read_b128 v[142:145], v146 offset:2048
	ds_read_b128 v[146:149], v146 offset:3072
	v_cndmask_b32_e32 v205, v151, v132, vcc
	v_cndmask_b32_e32 v204, v150, v133, vcc
	ds_read_b128 v[150:153], v162
	ds_read_b128 v[154:157], v162 offset:1024
	ds_read_b128 v[158:161], v162 offset:2048
	ds_read_b128 v[162:165], v162 offset:3072
	v_lshl_add_u64 v[212:213], s[12:13], 0, v[130:131]
	s_add_i32 m0, s20, 0xc000
	ds_read_b128 v[166:169], v227
	ds_read_b128 v[170:173], v227 offset:1024
	ds_read_b128 v[174:177], v227 offset:2048
	ds_read_b128 v[178:181], v227 offset:3072
	ds_read_b128 v[230:233], v227 offset:4096
	ds_read_b128 v[234:237], v227 offset:5120
	ds_read_b128 v[238:241], v227 offset:6144
	ds_read_b128 v[242:245], v227 offset:7168
	global_load_lds_dwordx4 v[212:213], off
	v_lshl_add_u64 v[212:213], s[12:13], 0, v[128:129]
	s_add_i32 m0, s20, 0xe000
	s_nop 0
	global_load_lds_dwordx4 v[212:213], off
	s_waitcnt vmcnt(8)
	s_waitcnt lgkmcnt(0)
	s_barrier
	s_setprio 1
	s_waitcnt lgkmcnt(0)
	v_mfma_f32_16x16x32_bf16 v[124:127], v[134:137], v[166:169], v[124:127]
	v_mfma_f32_16x16x32_bf16 v[0:3], v[142:145], v[166:169], v[0:3]
	v_mfma_f32_16x16x32_bf16 v[120:123], v[134:137], v[174:177], v[120:123]
	v_mfma_f32_16x16x32_bf16 v[116:119], v[142:145], v[174:177], v[116:119]
	v_mfma_f32_16x16x32_bf16 v[112:115], v[134:137], v[230:233], v[112:115]
	v_mfma_f32_16x16x32_bf16 v[108:111], v[142:145], v[230:233], v[108:111]
	v_mfma_f32_16x16x32_bf16 v[104:107], v[134:137], v[238:241], v[104:107]
	v_mfma_f32_16x16x32_bf16 v[4:7], v[142:145], v[238:241], v[4:7]
	v_mfma_f32_16x16x32_bf16 v[124:127], v[138:141], v[170:173], v[124:127]
	v_mfma_f32_16x16x32_bf16 v[0:3], v[146:149], v[170:173], v[0:3]
	v_mfma_f32_16x16x32_bf16 v[120:123], v[138:141], v[178:181], v[120:123]
	v_mfma_f32_16x16x32_bf16 v[116:119], v[146:149], v[178:181], v[116:119]
	v_mfma_f32_16x16x32_bf16 v[112:115], v[138:141], v[234:237], v[112:115]
	v_mfma_f32_16x16x32_bf16 v[108:111], v[146:149], v[234:237], v[108:111]
	v_mfma_f32_16x16x32_bf16 v[104:107], v[138:141], v[242:245], v[104:107]
	v_mfma_f32_16x16x32_bf16 v[4:7], v[146:149], v[242:245], v[4:7]
	s_setprio 0
	s_setprio 1
	v_mfma_f32_16x16x32_bf16 v[100:103], v[150:153], v[166:169], v[100:103]
	v_mfma_f32_16x16x32_bf16 v[96:99], v[158:161], v[166:169], v[96:99]
	v_mfma_f32_16x16x32_bf16 v[92:95], v[150:153], v[174:177], v[92:95]
	v_mfma_f32_16x16x32_bf16 v[88:91], v[158:161], v[174:177], v[88:91]
	v_mfma_f32_16x16x32_bf16 v[84:87], v[150:153], v[230:233], v[84:87]
	v_mfma_f32_16x16x32_bf16 v[80:83], v[158:161], v[230:233], v[80:83]
	v_mfma_f32_16x16x32_bf16 v[76:79], v[150:153], v[238:241], v[76:79]
	v_mfma_f32_16x16x32_bf16 v[72:75], v[158:161], v[238:241], v[72:75]
	v_mfma_f32_16x16x32_bf16 v[100:103], v[154:157], v[170:173], v[100:103]
	v_mfma_f32_16x16x32_bf16 v[96:99], v[162:165], v[170:173], v[96:99]
	v_mfma_f32_16x16x32_bf16 v[92:95], v[154:157], v[178:181], v[92:95]
	v_mfma_f32_16x16x32_bf16 v[88:91], v[162:165], v[178:181], v[88:91]
	v_mfma_f32_16x16x32_bf16 v[84:87], v[154:157], v[234:237], v[84:87]
	v_mfma_f32_16x16x32_bf16 v[80:83], v[162:165], v[234:237], v[80:83]
	v_mfma_f32_16x16x32_bf16 v[76:79], v[154:157], v[242:245], v[76:79]
	v_mfma_f32_16x16x32_bf16 v[72:75], v[162:165], v[242:245], v[72:75]
	s_setprio 0
	s_barrier
	s_add_i32 s27, s27, s11
	v_lshl_add_u64 v[212:213], v[204:205], 0, v[192:193]
	s_mov_b32 m0, s27
	ds_read_b128 v[166:169], v227 offset:16384
	ds_read_b128 v[170:173], v227 offset:17408
	ds_read_b128 v[174:177], v227 offset:18432
	ds_read_b128 v[178:181], v227 offset:19456
	ds_read_b128 v[230:233], v227 offset:20480
	ds_read_b128 v[234:237], v227 offset:21504
	ds_read_b128 v[238:241], v227 offset:22528
	ds_read_b128 v[242:245], v227 offset:23552
	global_load_lds_dwordx4 v[212:213], off
	v_lshl_add_u64 v[218:219], v[204:205], 0, v[196:197]
	s_add_i32 m0, s27, 0x2000
	v_lshl_add_u64 v[204:205], v[204:205], 0, v[198:199]
	s_add_i32 s26, s26, s11
	global_load_lds_dwordx4 v[218:219], off
	v_lshl_add_u64 v[246:247], v[204:205], 0, v[192:193]
	s_mov_b32 m0, s26
	v_lshl_add_u64 v[204:205], v[204:205], 0, v[196:197]
	global_load_lds_dwordx4 v[246:247], off
	s_add_i32 m0, s26, 0x2000
	v_lshl_add_u64 v[248:249], s[8:9], 0, v[190:191]
	global_load_lds_dwordx4 v[204:205], off
	s_mov_b32 m0, s20
	v_lshl_add_u64 v[250:251], s[8:9], 0, v[194:195]
	global_load_lds_dwordx4 v[248:249], off
	s_mov_b32 m0, s48
	s_nop 0
	global_load_lds_dwordx4 v[250:251], off
	s_waitcnt vmcnt(8)
	s_waitcnt lgkmcnt(0)
	s_barrier
; #define PG8_STAGE(bufoff, gbase, voff) do { _Pragma("unroll") for (int _i = 0; _i < 2; ++_i) \
;         __builtin_amdgcn_global_load_lds((const unsigned*)((const char*)(gbase) + (voff)[_i]), (LAS unsigned*)(lds + (bufoff) + ldsw + _i * 8192), 16, 0, 0); } while (0)
; #define PG8_LDA(dst, b, h) do { _Pragma("unroll") for (int m = 0; m < 4; ++m) _Pragma("unroll") for (int k = 0; k < 2; ++k) dst[m][k] = *(const LAS bf16x8*)(lds + PG8_SA(b, h) + aoff + m * 2048 + k * 1024); } while (0)
; #define PG8_LDB(dst, b, h) do { _Pragma("unroll") for (int n = 0; n < 2; ++n) _Pragma("unroll") for (int k = 0; k < 2; ++k) dst[n][k] = *(const LAS bf16x8*)(lds + PG8_SB(b, h) + boff + n * 2048 + k * 1024); } while (0)
; #define PG8_MMA(ai, bj, At, Bt) do { __builtin_amdgcn_s_setprio(1); _Pragma("unroll") for (int m = 0; m < 4; ++m) _Pragma("unroll") for (int n = 0; n < 2; ++n) _Pragma("unroll") for (int k = 0; k < 2; ++k) \
;         acc[ai][bj][m][n] = __builtin_amdgcn_mfma_f32_16x16x32_bf16(Bt[n][k], At[m][k], acc[ai][bj][m][n], 0, 0, 0); __builtin_amdgcn_s_setprio(0); } while (0)
; #define PG8_WAIT_V(n) asm volatile("s_waitcnt vmcnt(" #n ")" ::: "memory")
; #define PG8_WAIT_L(n) asm volatile("s_waitcnt lgkmcnt(" #n ")" ::: "memory")
; #define PG8_BAR __builtin_amdgcn_s_barrier()
; #define PG8_SCHED __builtin_amdgcn_sched_barrier(0)
;     ...
;             PG8_WAIT_V(8); PG8_WAIT_L(0); PG8_BAR; PG8_MMA(1, 0, At, B0); PG8_MMA(1, 1, At, B1); PG8_BAR; PG8_SCHED;
;             PG8_LDB(B0, 1, 0); PG8_LDB(B1, 1, 1); PG8_SCHED; PG8_LDA(At, 1, 0); PG8_STAGE(PG8_SA(0, 1), a2 + hstepA, voffA);
;             PG8_WAIT_V(8); PG8_WAIT_L(0); PG8_BAR; PG8_MMA(0, 0, At, B0); PG8_MMA(0, 1, At, B1); PG8_BAR; PG8_SCHED;
	s_setprio 1
	s_waitcnt lgkmcnt(0)
	v_mfma_f32_16x16x32_bf16 v[68:71], v[134:137], v[166:169], v[68:71]
	v_mfma_f32_16x16x32_bf16 v[8:11], v[142:145], v[166:169], v[8:11]
	v_mfma_f32_16x16x32_bf16 v[64:67], v[134:137], v[174:177], v[64:67]
	v_mfma_f32_16x16x32_bf16 v[60:63], v[142:145], v[174:177], v[60:63]
	v_mfma_f32_16x16x32_bf16 v[56:59], v[134:137], v[230:233], v[56:59]
	v_mfma_f32_16x16x32_bf16 v[52:55], v[142:145], v[230:233], v[52:55]
	v_mfma_f32_16x16x32_bf16 v[48:51], v[134:137], v[238:241], v[48:51]
	v_mfma_f32_16x16x32_bf16 v[12:15], v[142:145], v[238:241], v[12:15]
	v_mfma_f32_16x16x32_bf16 v[68:71], v[138:141], v[170:173], v[68:71]
	v_mfma_f32_16x16x32_bf16 v[8:11], v[146:149], v[170:173], v[8:11]
	v_mfma_f32_16x16x32_bf16 v[64:67], v[138:141], v[178:181], v[64:67]
	v_mfma_f32_16x16x32_bf16 v[60:63], v[146:149], v[178:181], v[60:63]
	v_mfma_f32_16x16x32_bf16 v[56:59], v[138:141], v[234:237], v[56:59]
	v_mfma_f32_16x16x32_bf16 v[52:55], v[146:149], v[234:237], v[52:55]
	v_mfma_f32_16x16x32_bf16 v[48:51], v[138:141], v[242:245], v[48:51]
	v_mfma_f32_16x16x32_bf16 v[12:15], v[146:149], v[242:245], v[12:15]
	s_setprio 0
	s_setprio 1
	v_mfma_f32_16x16x32_bf16 v[44:47], v[150:153], v[166:169], v[44:47]
	v_mfma_f32_16x16x32_bf16 v[40:43], v[158:161], v[166:169], v[40:43]
	v_mfma_f32_16x16x32_bf16 v[36:39], v[150:153], v[174:177], v[36:39]
	v_mfma_f32_16x16x32_bf16 v[32:35], v[158:161], v[174:177], v[32:35]
	v_mfma_f32_16x16x32_bf16 v[28:31], v[150:153], v[230:233], v[28:31]
	v_mfma_f32_16x16x32_bf16 v[24:27], v[158:161], v[230:233], v[24:27]
	v_mfma_f32_16x16x32_bf16 v[20:23], v[150:153], v[238:241], v[20:23]
	v_mfma_f32_16x16x32_bf16 v[16:19], v[158:161], v[238:241], v[16:19]
	v_mfma_f32_16x16x32_bf16 v[44:47], v[154:157], v[170:173], v[44:47]
	v_mfma_f32_16x16x32_bf16 v[40:43], v[162:165], v[170:173], v[40:43]
	v_mfma_f32_16x16x32_bf16 v[36:39], v[154:157], v[178:181], v[36:39]
	v_mfma_f32_16x16x32_bf16 v[32:35], v[162:165], v[178:181], v[32:35]
	v_mfma_f32_16x16x32_bf16 v[28:31], v[154:157], v[234:237], v[28:31]
	v_mfma_f32_16x16x32_bf16 v[24:27], v[162:165], v[234:237], v[24:27]
	v_mfma_f32_16x16x32_bf16 v[20:23], v[154:157], v[242:245], v[20:23]
	v_mfma_f32_16x16x32_bf16 v[16:19], v[162:165], v[242:245], v[16:19]
	s_setprio 0
	s_barrier
	s_add_i32 s26, 0, 0x18000
	s_add_i32 s27, 0, 0x1c000
	v_add_u32_e32 v146, s26, v226
	v_add_u32_e32 v162, s27, v226
	ds_read_b128 v[134:137], v146
	ds_read_b128 v[138:141], v146 offset:1024
	ds_read_b128 v[142:145], v146 offset:2048
	ds_read_b128 v[146:149], v146 offset:3072
	ds_read_b128 v[150:153], v162
	ds_read_b128 v[154:157], v162 offset:1024
	ds_read_b128 v[158:161], v162 offset:2048
	ds_read_b128 v[162:165], v162 offset:3072
	s_add_u32 s8, s8, s10
	s_addc_u32 s9, s9, 0
	s_mov_b32 m0, s51
	v_lshl_add_u64 v[214:215], s[8:9], 0, v[190:191]
	ds_read_b128 v[166:169], v227 offset:32768
	ds_read_b128 v[170:173], v227 offset:33792
	ds_read_b128 v[174:177], v227 offset:34816
	ds_read_b128 v[178:181], v227 offset:35840
	ds_read_b128 v[230:233], v227 offset:36864
	ds_read_b128 v[234:237], v227 offset:37888
	ds_read_b128 v[238:241], v227 offset:38912
	ds_read_b128 v[242:245], v227 offset:39936
	global_load_lds_dwordx4 v[214:215], off
	v_lshl_add_u64 v[214:215], s[8:9], 0, v[194:195]
	s_mov_b32 m0, s62
	s_nop 0
	global_load_lds_dwordx4 v[214:215], off
	s_waitcnt vmcnt(8)
	s_waitcnt lgkmcnt(0)
	s_barrier
	s_setprio 1
	s_waitcnt lgkmcnt(0)
	v_mfma_f32_16x16x32_bf16 v[124:127], v[134:137], v[166:169], v[124:127]
	v_mfma_f32_16x16x32_bf16 v[0:3], v[142:145], v[166:169], v[0:3]
	v_mfma_f32_16x16x32_bf16 v[120:123], v[134:137], v[174:177], v[120:123]
	v_mfma_f32_16x16x32_bf16 v[116:119], v[142:145], v[174:177], v[116:119]
	v_mfma_f32_16x16x32_bf16 v[112:115], v[134:137], v[230:233], v[112:115]
	v_mfma_f32_16x16x32_bf16 v[108:111], v[142:145], v[230:233], v[108:111]
	v_mfma_f32_16x16x32_bf16 v[104:107], v[134:137], v[238:241], v[104:107]
	v_mfma_f32_16x16x32_bf16 v[4:7], v[142:145], v[238:241], v[4:7]
	v_mfma_f32_16x16x32_bf16 v[124:127], v[138:141], v[170:173], v[124:127]
	v_mfma_f32_16x16x32_bf16 v[0:3], v[146:149], v[170:173], v[0:3]
	v_mfma_f32_16x16x32_bf16 v[120:123], v[138:141], v[178:181], v[120:123]
	v_mfma_f32_16x16x32_bf16 v[116:119], v[146:149], v[178:181], v[116:119]
	v_mfma_f32_16x16x32_bf16 v[112:115], v[138:141], v[234:237], v[112:115]
	v_mfma_f32_16x16x32_bf16 v[108:111], v[146:149], v[234:237], v[108:111]
	v_mfma_f32_16x16x32_bf16 v[104:107], v[138:141], v[242:245], v[104:107]
	v_mfma_f32_16x16x32_bf16 v[4:7], v[146:149], v[242:245], v[4:7]
	s_setprio 0
	s_setprio 1
	v_mfma_f32_16x16x32_bf16 v[100:103], v[150:153], v[166:169], v[100:103]
	v_mfma_f32_16x16x32_bf16 v[96:99], v[158:161], v[166:169], v[96:99]
	v_mfma_f32_16x16x32_bf16 v[92:95], v[150:153], v[174:177], v[92:95]
	v_mfma_f32_16x16x32_bf16 v[88:91], v[158:161], v[174:177], v[88:91]
	v_mfma_f32_16x16x32_bf16 v[84:87], v[150:153], v[230:233], v[84:87]
	v_mfma_f32_16x16x32_bf16 v[80:83], v[158:161], v[230:233], v[80:83]
	v_mfma_f32_16x16x32_bf16 v[76:79], v[150:153], v[238:241], v[76:79]
	v_mfma_f32_16x16x32_bf16 v[72:75], v[158:161], v[238:241], v[72:75]
	v_mfma_f32_16x16x32_bf16 v[100:103], v[154:157], v[170:173], v[100:103]
	v_mfma_f32_16x16x32_bf16 v[96:99], v[162:165], v[170:173], v[96:99]
	v_mfma_f32_16x16x32_bf16 v[92:95], v[154:157], v[178:181], v[92:95]
	v_mfma_f32_16x16x32_bf16 v[88:91], v[162:165], v[178:181], v[88:91]
	v_mfma_f32_16x16x32_bf16 v[84:87], v[154:157], v[234:237], v[84:87]
	v_mfma_f32_16x16x32_bf16 v[80:83], v[162:165], v[234:237], v[80:83]
	v_mfma_f32_16x16x32_bf16 v[76:79], v[154:157], v[242:245], v[76:79]
	v_mfma_f32_16x16x32_bf16 v[72:75], v[162:165], v[242:245], v[72:75]
	s_setprio 0
	s_barrier
; #define PG8_STAGE(bufoff, gbase, voff) do { _Pragma("unroll") for (int _i = 0; _i < 2; ++_i) \
;         __builtin_amdgcn_global_load_lds((const unsigned*)((const char*)(gbase) + (voff)[_i]), (LAS unsigned*)(lds + (bufoff) + ldsw + _i * 8192), 16, 0, 0); } while (0)
; #define PG8_LDA(dst, b, h) do { _Pragma("unroll") for (int m = 0; m < 4; ++m) _Pragma("unroll") for (int k = 0; k < 2; ++k) dst[m][k] = *(const LAS bf16x8*)(lds + PG8_SA(b, h) + aoff + m * 2048 + k * 1024); } while (0)
; #define PG8_MMA(ai, bj, At, Bt) do { __builtin_amdgcn_s_setprio(1); _Pragma("unroll") for (int m = 0; m < 4; ++m) _Pragma("unroll") for (int n = 0; n < 2; ++n) _Pragma("unroll") for (int k = 0; k < 2; ++k) \
;         acc[ai][bj][m][n] = __builtin_amdgcn_mfma_f32_16x16x32_bf16(Bt[n][k], At[m][k], acc[ai][bj][m][n], 0, 0, 0); __builtin_amdgcn_s_setprio(0); } while (0)
; #define PG8_WAIT_V(n) asm volatile("s_waitcnt vmcnt(" #n ")" ::: "memory")
; #define PG8_WAIT_L(n) asm volatile("s_waitcnt lgkmcnt(" #n ")" ::: "memory")
; #define PG8_BAR __builtin_amdgcn_s_barrier()
; #define PG8_SCHED __builtin_amdgcn_sched_barrier(0)
;     ...
;             PG8_LDA(At, 1, 1); PG8_STAGE(PG8_SB(1, 0), b3, voffB); PG8_STAGE(PG8_SB(1, 1), b3 + hstepB, voffB); PG8_STAGE(PG8_SA(1, 0), a3, voffA);
;             PG8_WAIT_V(8); PG8_WAIT_L(0); PG8_BAR; PG8_MMA(1, 0, At, B0); PG8_MMA(1, 1, At, B1); PG8_BAR; PG8_SCHED;
;         }
;         if (wr == 0) PG8_BAR;
	s_nop 0
	s_add_i32 s8, s26, s11
	s_add_i32 m0, s8, 0xffffff80
	ds_read_b128 v[166:169], v227 offset:49152
	ds_read_b128 v[170:173], v227 offset:50176
	ds_read_b128 v[174:177], v227 offset:51200
	ds_read_b128 v[178:181], v227 offset:52224
	ds_read_b128 v[230:233], v227 offset:53248
	ds_read_b128 v[234:237], v227 offset:54272
	ds_read_b128 v[238:241], v227 offset:55296
	ds_read_b128 v[242:245], v227 offset:56320
	global_load_lds_dwordx4 v[212:213], off offset:128
	s_add_i32 m0, s8, 0x1f80
	s_add_i32 s8, s27, s11
	global_load_lds_dwordx4 v[218:219], off offset:128
	s_add_i32 m0, s8, 0xffffff80
	s_nop 0
	global_load_lds_dwordx4 v[246:247], off offset:128
	s_add_i32 m0, s8, 0x1f80
	s_nop 0
	global_load_lds_dwordx4 v[204:205], off offset:128
	s_add_i32 m0, s65, 0xffffff80
	s_nop 0
	global_load_lds_dwordx4 v[248:249], off offset:128
	s_add_i32 m0, s49, 0xffffff80
	s_nop 0
	global_load_lds_dwordx4 v[250:251], off offset:128
	s_waitcnt vmcnt(8)
	s_waitcnt lgkmcnt(0)
	s_barrier
	s_setprio 1
	s_waitcnt lgkmcnt(0)
	v_mfma_f32_16x16x32_bf16 v[68:71], v[134:137], v[166:169], v[68:71]
	v_mfma_f32_16x16x32_bf16 v[8:11], v[142:145], v[166:169], v[8:11]
	v_mfma_f32_16x16x32_bf16 v[64:67], v[134:137], v[174:177], v[64:67]
	v_mfma_f32_16x16x32_bf16 v[60:63], v[142:145], v[174:177], v[60:63]
	v_mfma_f32_16x16x32_bf16 v[56:59], v[134:137], v[230:233], v[56:59]
	v_mfma_f32_16x16x32_bf16 v[52:55], v[142:145], v[230:233], v[52:55]
	v_mfma_f32_16x16x32_bf16 v[48:51], v[134:137], v[238:241], v[48:51]
	v_mfma_f32_16x16x32_bf16 v[12:15], v[142:145], v[238:241], v[12:15]
	v_mfma_f32_16x16x32_bf16 v[68:71], v[138:141], v[170:173], v[68:71]
	v_mfma_f32_16x16x32_bf16 v[8:11], v[146:149], v[170:173], v[8:11]
	v_mfma_f32_16x16x32_bf16 v[64:67], v[138:141], v[178:181], v[64:67]
	v_mfma_f32_16x16x32_bf16 v[60:63], v[146:149], v[178:181], v[60:63]
	v_mfma_f32_16x16x32_bf16 v[56:59], v[138:141], v[234:237], v[56:59]
	v_mfma_f32_16x16x32_bf16 v[52:55], v[146:149], v[234:237], v[52:55]
	v_mfma_f32_16x16x32_bf16 v[48:51], v[138:141], v[242:245], v[48:51]
	v_mfma_f32_16x16x32_bf16 v[12:15], v[146:149], v[242:245], v[12:15]
	s_setprio 0
	s_setprio 1
	v_mfma_f32_16x16x32_bf16 v[44:47], v[150:153], v[166:169], v[44:47]
	v_mfma_f32_16x16x32_bf16 v[40:43], v[158:161], v[166:169], v[40:43]
	v_mfma_f32_16x16x32_bf16 v[36:39], v[150:153], v[174:177], v[36:39]
	v_mfma_f32_16x16x32_bf16 v[32:35], v[158:161], v[174:177], v[32:35]
	v_mfma_f32_16x16x32_bf16 v[28:31], v[150:153], v[230:233], v[28:31]
	v_mfma_f32_16x16x32_bf16 v[24:27], v[158:161], v[230:233], v[24:27]
	v_mfma_f32_16x16x32_bf16 v[20:23], v[150:153], v[238:241], v[20:23]
	v_mfma_f32_16x16x32_bf16 v[16:19], v[158:161], v[238:241], v[16:19]
	v_mfma_f32_16x16x32_bf16 v[44:47], v[154:157], v[170:173], v[44:47]
	v_mfma_f32_16x16x32_bf16 v[40:43], v[162:165], v[170:173], v[40:43]
	v_mfma_f32_16x16x32_bf16 v[36:39], v[154:157], v[178:181], v[36:39]
	v_mfma_f32_16x16x32_bf16 v[32:35], v[162:165], v[178:181], v[32:35]
	v_mfma_f32_16x16x32_bf16 v[28:31], v[154:157], v[234:237], v[28:31]
	v_mfma_f32_16x16x32_bf16 v[24:27], v[162:165], v[234:237], v[24:27]
	v_mfma_f32_16x16x32_bf16 v[20:23], v[154:157], v[242:245], v[20:23]
	v_mfma_f32_16x16x32_bf16 v[16:19], v[162:165], v[242:245], v[16:19]
	s_setprio 0
	s_barrier
	s_add_u32 s0, s0, 0x100
	s_addc_u32 s1, s1, 0
	v_lshl_add_u64 v[130:131], v[130:131], 0, s[94:95]
	v_lshl_add_u64 v[128:129], v[128:129], 0, s[94:95]
	s_cmp_ge_u32 s38, s52
	s_mov_b32 s8, s38
	s_cbranch_scc0 .LBB0_159
	v_readlane_b32 s0, v254, 50
	v_readlane_b32 s1, v254, 51
	s_and_b64 vcc, exec, s[0:1]
	s_movk_i32 s67, 0xfe
	s_cbranch_vccz .LBB0_162
	s_barrier

; #define PG8_STAGE(bufoff, gbase, voff) do { _Pragma("unroll") for (int _i = 0; _i < 2; ++_i) \
;         __builtin_amdgcn_global_load_lds((const unsigned*)((const char*)(gbase) + (voff)[_i]), (LAS unsigned*)(lds + (bufoff) + ldsw + _i * 8192), 16, 0, 0); } while (0)
; #define PG8_LDA(dst, b, h) do { _Pragma("unroll") for (int m = 0; m < 4; ++m) _Pragma("unroll") for (int k = 0; k < 2; ++k) dst[m][k] = *(const LAS bf16x8*)(lds + PG8_SA(b, h) + aoff + m * 2048 + k * 1024); } while (0)
; #define PG8_LDB(dst, b, h) do { _Pragma("unroll") for (int n = 0; n < 2; ++n) _Pragma("unroll") for (int k = 0; k < 2; ++k) dst[n][k] = *(const LAS bf16x8*)(lds + PG8_SB(b, h) + boff + n * 2048 + k * 1024); } while (0)
; #define PG8_MMA(ai, bj, At, Bt) do { __builtin_amdgcn_s_setprio(1); _Pragma("unroll") for (int m = 0; m < 4; ++m) _Pragma("unroll") for (int n = 0; n < 2; ++n) _Pragma("unroll") for (int k = 0; k < 2; ++k) \
;         acc[ai][bj][m][n] = __builtin_amdgcn_mfma_f32_16x16x32_bf16(Bt[n][k], At[m][k], acc[ai][bj][m][n], 0, 0, 0); __builtin_amdgcn_s_setprio(0); } while (0)
; #define PG8_WAIT_V(n) asm volatile("s_waitcnt vmcnt(" #n ")" ::: "memory")
; #define PG8_WAIT_L(n) asm volatile("s_waitcnt lgkmcnt(" #n ")" ::: "memory")
; #define PG8_BAR __builtin_amdgcn_s_barrier()
; #define PG8_SCHED __builtin_amdgcn_sched_barrier(0)
;     ...
;         const bool has_next = S.next(ui + 1, nxt);
;         const char* nA = has_next ? nxt.A : cA; const char* nB = has_next ? nxt.B : cB;
;         for (int t = 0; t < nt; t += 2) {
;             const bool last = (t == nt - 2);
;             const char* a1 = cA + (size_t)(t + 1) * kstep;
;             const char* a2 = last ? nA : cA + (size_t)(t + 2) * kstep; const char* b2 = last ? nB : cB + (size_t)(t + 2) * kstep;
;             const char* a3 = a2 + kstep; const char* b3 = b2 + kstep;
;             PG8_LDB(B0, 0, 0); PG8_LDB(B1, 0, 1); PG8_SCHED; PG8_LDA(At, 0, 0); PG8_STAGE(PG8_SA(1, 1), a1 + hstepA, voffA);
;             PG8_WAIT_V(8); PG8_WAIT_L(0); PG8_BAR; PG8_MMA(0, 0, At, B0); PG8_MMA(0, 1, At, B1); PG8_BAR; PG8_SCHED;
;             PG8_LDA(At, 0, 1); PG8_STAGE(PG8_SB(0, 0), b2, voffB); PG8_STAGE(PG8_SB(0, 1), b2 + hstepB, voffB); PG8_STAGE(PG8_SA(0, 0), a2, voffA);
;             PG8_WAIT_V(8); PG8_WAIT_L(0); PG8_BAR; PG8_MMA(1, 0, At, B0); PG8_MMA(1, 1, At, B1); PG8_BAR; PG8_SCHED;
.LBB0_317:
	s_mov_b64 s[54:55], s[68:69]
	v_mov_b32_e32 v189, v128
	s_xor_b64 s[66:67], s[64:65], -1
	v_mov_b32_e32 v128, s55
	s_mov_b64 s[36:37], s[38:39]
	s_and_b64 s[0:1], s[64:65], exec
	v_cndmask_b32_e64 v132, v161, v128, s[64:65]
	v_mov_b32_e32 v128, s54
	s_mov_b64 s[6:7], s[56:57]
	s_mov_b64 s[14:15], s[58:59]
	s_mov_b32 s26, s19
	s_cselect_b32 s13, s37, s3
	s_cselect_b32 s56, s36, s2
	v_cndmask_b32_e64 v133, v160, v128, s[64:65]
	s_mov_b32 s38, 0
	s_mov_b64 s[0:1], 0x100
	v_mov_b64_e32 v[128:129], v[172:173]
	v_mov_b64_e32 v[130:131], v[170:171]
	s_nop 0
	s_nop 0
	s_nop 0
	s_nop 0
	s_nop 0
	s_nop 0
	s_nop 0
	s_nop 0
	s_nop 0
	s_nop 0
.LBB0_318:
	s_add_i32 s57, s38, 2
	s_add_u32 s19, s2, s0
	s_addc_u32 s27, s3, s1
	s_add_i32 s58, 0, 0x10000
	s_cmp_eq_u32 s51, s38
	s_cselect_b32 s39, s13, s27
	s_cselect_b32 s38, s56, s19
	s_cselect_b64 vcc, -1, 0
	s_add_i32 s19, 0, 0x14000
	v_lshl_add_u64 v[150:151], v[160:161], 0, s[0:1]
	v_add_u32_e32 v146, s58, v181
	s_waitcnt lgkmcnt(0)
	v_add_u32_e32 v178, s19, v181
	ds_read_b128 v[134:137], v146
	ds_read_b128 v[138:141], v146 offset:1024
	ds_read_b128 v[142:145], v146 offset:2048
	ds_read_b128 v[146:149], v146 offset:3072
	v_cndmask_b32_e32 v159, v151, v132, vcc
	v_cndmask_b32_e32 v158, v150, v133, vcc
	ds_read_b128 v[150:153], v178
	ds_read_b128 v[154:157], v178 offset:1024
	ds_read_b128 v[174:177], v178 offset:2048
	ds_read_b128 v[190:193], v178 offset:3072
	v_lshl_add_u64 v[178:179], s[2:3], 0, v[130:131]
	s_add_i32 m0, s11, 0xc000
	ds_read_b128 v[194:197], v188
	ds_read_b128 v[198:201], v188 offset:1024
	ds_read_b128 v[202:205], v188 offset:2048
	ds_read_b128 v[224:227], v188 offset:3072
	ds_read_b128 v[228:231], v188 offset:4096
	ds_read_b128 v[232:235], v188 offset:5120
	ds_read_b128 v[236:239], v188 offset:6144
	ds_read_b128 v[240:243], v188 offset:7168
	global_load_lds_dwordx4 v[178:179], off
	v_lshl_add_u64 v[178:179], s[2:3], 0, v[128:129]
	s_add_i32 m0, s11, 0xe000
	s_nop 0
	global_load_lds_dwordx4 v[178:179], off
	s_waitcnt vmcnt(8)
	s_waitcnt lgkmcnt(0)
	s_barrier
	s_setprio 1
	s_waitcnt lgkmcnt(0)
	v_mfma_f32_16x16x32_bf16 v[124:127], v[134:137], v[194:197], v[124:127]
	v_mfma_f32_16x16x32_bf16 v[120:123], v[142:145], v[194:197], v[120:123]
	v_mfma_f32_16x16x32_bf16 v[116:119], v[134:137], v[202:205], v[116:119]
	v_mfma_f32_16x16x32_bf16 v[112:115], v[142:145], v[202:205], v[112:115]
	v_mfma_f32_16x16x32_bf16 v[108:111], v[134:137], v[228:231], v[108:111]
	v_mfma_f32_16x16x32_bf16 v[104:107], v[142:145], v[228:231], v[104:107]
	v_mfma_f32_16x16x32_bf16 v[100:103], v[134:137], v[236:239], v[100:103]
	v_mfma_f32_16x16x32_bf16 v[96:99], v[142:145], v[236:239], v[96:99]
	v_mfma_f32_16x16x32_bf16 v[124:127], v[138:141], v[198:201], v[124:127]
	v_mfma_f32_16x16x32_bf16 v[120:123], v[146:149], v[198:201], v[120:123]
	v_mfma_f32_16x16x32_bf16 v[116:119], v[138:141], v[224:227], v[116:119]
	v_mfma_f32_16x16x32_bf16 v[112:115], v[146:149], v[224:227], v[112:115]
	v_mfma_f32_16x16x32_bf16 v[108:111], v[138:141], v[232:235], v[108:111]
	v_mfma_f32_16x16x32_bf16 v[104:107], v[146:149], v[232:235], v[104:107]
	v_mfma_f32_16x16x32_bf16 v[100:103], v[138:141], v[240:243], v[100:103]
	v_mfma_f32_16x16x32_bf16 v[96:99], v[146:149], v[240:243], v[96:99]
	s_setprio 0
	s_setprio 1
	v_mfma_f32_16x16x32_bf16 v[92:95], v[150:153], v[194:197], v[92:95]
	v_mfma_f32_16x16x32_bf16 v[88:91], v[174:177], v[194:197], v[88:91]
	v_mfma_f32_16x16x32_bf16 v[84:87], v[150:153], v[202:205], v[84:87]
	v_mfma_f32_16x16x32_bf16 v[80:83], v[174:177], v[202:205], v[80:83]
	v_mfma_f32_16x16x32_bf16 v[76:79], v[150:153], v[228:231], v[76:79]
	v_mfma_f32_16x16x32_bf16 v[72:75], v[174:177], v[228:231], v[72:75]
	v_mfma_f32_16x16x32_bf16 v[68:71], v[150:153], v[236:239], v[68:71]
	v_mfma_f32_16x16x32_bf16 v[64:67], v[174:177], v[236:239], v[64:67]
	v_mfma_f32_16x16x32_bf16 v[92:95], v[154:157], v[198:201], v[92:95]
	v_mfma_f32_16x16x32_bf16 v[88:91], v[190:193], v[198:201], v[88:91]
	v_mfma_f32_16x16x32_bf16 v[84:87], v[154:157], v[224:227], v[84:87]
	v_mfma_f32_16x16x32_bf16 v[80:83], v[190:193], v[224:227], v[80:83]
	v_mfma_f32_16x16x32_bf16 v[76:79], v[154:157], v[232:235], v[76:79]
	v_mfma_f32_16x16x32_bf16 v[72:75], v[190:193], v[232:235], v[72:75]
	v_mfma_f32_16x16x32_bf16 v[68:71], v[154:157], v[240:243], v[68:71]
	v_mfma_f32_16x16x32_bf16 v[64:67], v[190:193], v[240:243], v[64:67]
	s_setprio 0
	s_barrier
	s_add_i32 s27, s58, s10
	v_lshl_add_u64 v[178:179], v[158:159], 0, v[164:165]
	s_mov_b32 m0, s27
	ds_read_b128 v[194:197], v188 offset:16384
	ds_read_b128 v[198:201], v188 offset:17408
	ds_read_b128 v[202:205], v188 offset:18432
	ds_read_b128 v[224:227], v188 offset:19456
	ds_read_b128 v[228:231], v188 offset:20480
	ds_read_b128 v[232:235], v188 offset:21504
	ds_read_b128 v[236:239], v188 offset:22528
	ds_read_b128 v[240:243], v188 offset:23552
	global_load_lds_dwordx4 v[178:179], off
	v_lshl_add_u64 v[212:213], v[158:159], 0, v[168:169]
	s_add_i32 m0, s27, 0x2000
	v_lshl_add_u64 v[158:159], v[158:159], 0, s[96:97]
	s_add_i32 s19, s19, s10
	global_load_lds_dwordx4 v[212:213], off
	v_lshl_add_u64 v[218:219], v[158:159], 0, v[164:165]
	s_mov_b32 m0, s19
	v_lshl_add_u64 v[158:159], v[158:159], 0, v[168:169]
	global_load_lds_dwordx4 v[218:219], off
	s_add_i32 m0, s19, 0x2000
	v_lshl_add_u64 v[244:245], s[38:39], 0, v[162:163]
	global_load_lds_dwordx4 v[158:159], off
	s_mov_b32 m0, s11
	v_lshl_add_u64 v[246:247], s[38:39], 0, v[166:167]
	global_load_lds_dwordx4 v[244:245], off
	s_mov_b32 m0, s20
	s_nop 0
	global_load_lds_dwordx4 v[246:247], off
	s_waitcnt vmcnt(8)
	s_waitcnt lgkmcnt(0)
	s_barrier
; #define PG8_STAGE(bufoff, gbase, voff) do { _Pragma("unroll") for (int _i = 0; _i < 2; ++_i) \
;         __builtin_amdgcn_global_load_lds((const unsigned*)((const char*)(gbase) + (voff)[_i]), (LAS unsigned*)(lds + (bufoff) + ldsw + _i * 8192), 16, 0, 0); } while (0)
; #define PG8_LDA(dst, b, h) do { _Pragma("unroll") for (int m = 0; m < 4; ++m) _Pragma("unroll") for (int k = 0; k < 2; ++k) dst[m][k] = *(const LAS bf16x8*)(lds + PG8_SA(b, h) + aoff + m * 2048 + k * 1024); } while (0)
; #define PG8_LDB(dst, b, h) do { _Pragma("unroll") for (int n = 0; n < 2; ++n) _Pragma("unroll") for (int k = 0; k < 2; ++k) dst[n][k] = *(const LAS bf16x8*)(lds + PG8_SB(b, h) + boff + n * 2048 + k * 1024); } while (0)
; #define PG8_MMA(ai, bj, At, Bt) do { __builtin_amdgcn_s_setprio(1); _Pragma("unroll") for (int m = 0; m < 4; ++m) _Pragma("unroll") for (int n = 0; n < 2; ++n) _Pragma("unroll") for (int k = 0; k < 2; ++k) \
;         acc[ai][bj][m][n] = __builtin_amdgcn_mfma_f32_16x16x32_bf16(Bt[n][k], At[m][k], acc[ai][bj][m][n], 0, 0, 0); __builtin_amdgcn_s_setprio(0); } while (0)
; #define PG8_WAIT_V(n) asm volatile("s_waitcnt vmcnt(" #n ")" ::: "memory")
; #define PG8_WAIT_L(n) asm volatile("s_waitcnt lgkmcnt(" #n ")" ::: "memory")
; #define PG8_BAR __builtin_amdgcn_s_barrier()
; #define PG8_SCHED __builtin_amdgcn_sched_barrier(0)
;     ...
;             PG8_WAIT_V(8); PG8_WAIT_L(0); PG8_BAR; PG8_MMA(1, 0, At, B0); PG8_MMA(1, 1, At, B1); PG8_BAR; PG8_SCHED;
;             PG8_LDB(B0, 1, 0); PG8_LDB(B1, 1, 1); PG8_SCHED; PG8_LDA(At, 1, 0); PG8_STAGE(PG8_SA(0, 1), a2 + hstepA, voffA);
;             PG8_WAIT_V(8); PG8_WAIT_L(0); PG8_BAR; PG8_MMA(0, 0, At, B0); PG8_MMA(0, 1, At, B1); PG8_BAR; PG8_SCHED;
	s_setprio 1
	s_waitcnt lgkmcnt(0)
	v_mfma_f32_16x16x32_bf16 v[60:63], v[134:137], v[194:197], v[60:63]
	v_mfma_f32_16x16x32_bf16 v[56:59], v[142:145], v[194:197], v[56:59]
	v_mfma_f32_16x16x32_bf16 v[52:55], v[134:137], v[202:205], v[52:55]
	v_mfma_f32_16x16x32_bf16 v[48:51], v[142:145], v[202:205], v[48:51]
	v_mfma_f32_16x16x32_bf16 v[44:47], v[134:137], v[228:231], v[44:47]
	v_mfma_f32_16x16x32_bf16 v[40:43], v[142:145], v[228:231], v[40:43]
	v_mfma_f32_16x16x32_bf16 v[36:39], v[134:137], v[236:239], v[36:39]
	v_mfma_f32_16x16x32_bf16 v[32:35], v[142:145], v[236:239], v[32:35]
	v_mfma_f32_16x16x32_bf16 v[60:63], v[138:141], v[198:201], v[60:63]
	v_mfma_f32_16x16x32_bf16 v[56:59], v[146:149], v[198:201], v[56:59]
	v_mfma_f32_16x16x32_bf16 v[52:55], v[138:141], v[224:227], v[52:55]
	v_mfma_f32_16x16x32_bf16 v[48:51], v[146:149], v[224:227], v[48:51]
	v_mfma_f32_16x16x32_bf16 v[44:47], v[138:141], v[232:235], v[44:47]
	v_mfma_f32_16x16x32_bf16 v[40:43], v[146:149], v[232:235], v[40:43]
	v_mfma_f32_16x16x32_bf16 v[36:39], v[138:141], v[240:243], v[36:39]
	v_mfma_f32_16x16x32_bf16 v[32:35], v[146:149], v[240:243], v[32:35]
	s_setprio 0
	s_setprio 1
	v_mfma_f32_16x16x32_bf16 v[28:31], v[150:153], v[194:197], v[28:31]
	v_mfma_f32_16x16x32_bf16 v[24:27], v[174:177], v[194:197], v[24:27]
	v_mfma_f32_16x16x32_bf16 v[20:23], v[150:153], v[202:205], v[20:23]
	v_mfma_f32_16x16x32_bf16 v[16:19], v[174:177], v[202:205], v[16:19]
	v_mfma_f32_16x16x32_bf16 v[12:15], v[150:153], v[228:231], v[12:15]
	v_mfma_f32_16x16x32_bf16 v[8:11], v[174:177], v[228:231], v[8:11]
	v_mfma_f32_16x16x32_bf16 v[4:7], v[150:153], v[236:239], v[4:7]
	v_mfma_f32_16x16x32_bf16 v[0:3], v[174:177], v[236:239], v[0:3]
	v_mfma_f32_16x16x32_bf16 v[28:31], v[154:157], v[198:201], v[28:31]
	v_mfma_f32_16x16x32_bf16 v[24:27], v[190:193], v[198:201], v[24:27]
	v_mfma_f32_16x16x32_bf16 v[20:23], v[154:157], v[224:227], v[20:23]
	v_mfma_f32_16x16x32_bf16 v[16:19], v[190:193], v[224:227], v[16:19]
	v_mfma_f32_16x16x32_bf16 v[12:15], v[154:157], v[232:235], v[12:15]
	v_mfma_f32_16x16x32_bf16 v[8:11], v[190:193], v[232:235], v[8:11]
	v_mfma_f32_16x16x32_bf16 v[4:7], v[154:157], v[240:243], v[4:7]
	v_mfma_f32_16x16x32_bf16 v[0:3], v[190:193], v[240:243], v[0:3]
	s_setprio 0
	s_barrier
	s_add_i32 s19, 0, 0x18000
	s_add_i32 s27, 0, 0x1c000
	v_add_u32_e32 v146, s19, v181
	v_add_u32_e32 v182, s27, v181
	ds_read_b128 v[134:137], v146
	ds_read_b128 v[138:141], v146 offset:1024
	ds_read_b128 v[142:145], v146 offset:2048
	ds_read_b128 v[146:149], v146 offset:3072
	ds_read_b128 v[150:153], v182
	ds_read_b128 v[154:157], v182 offset:1024
	ds_read_b128 v[174:177], v182 offset:2048
	ds_read_b128 v[190:193], v182 offset:3072
	s_add_u32 s38, s38, s96
	s_addc_u32 s39, s39, 0
	s_mov_b32 m0, s48
	v_lshl_add_u64 v[248:249], s[38:39], 0, v[162:163]
	ds_read_b128 v[194:197], v188 offset:32768
	ds_read_b128 v[198:201], v188 offset:33792
	ds_read_b128 v[202:205], v188 offset:34816
	ds_read_b128 v[224:227], v188 offset:35840
	ds_read_b128 v[228:231], v188 offset:36864
	ds_read_b128 v[232:235], v188 offset:37888
	ds_read_b128 v[236:239], v188 offset:38912
	ds_read_b128 v[240:243], v188 offset:39936
	global_load_lds_dwordx4 v[248:249], off
	v_lshl_add_u64 v[248:249], s[38:39], 0, v[166:167]
	s_mov_b32 m0, s49
	s_nop 0
	global_load_lds_dwordx4 v[248:249], off
	s_waitcnt vmcnt(8)
	s_waitcnt lgkmcnt(0)
	s_barrier
	s_setprio 1
	s_waitcnt lgkmcnt(0)
	v_mfma_f32_16x16x32_bf16 v[124:127], v[134:137], v[194:197], v[124:127]
	v_mfma_f32_16x16x32_bf16 v[120:123], v[142:145], v[194:197], v[120:123]
	v_mfma_f32_16x16x32_bf16 v[116:119], v[134:137], v[202:205], v[116:119]
	v_mfma_f32_16x16x32_bf16 v[112:115], v[142:145], v[202:205], v[112:115]
	v_mfma_f32_16x16x32_bf16 v[108:111], v[134:137], v[228:231], v[108:111]
	v_mfma_f32_16x16x32_bf16 v[104:107], v[142:145], v[228:231], v[104:107]
	v_mfma_f32_16x16x32_bf16 v[100:103], v[134:137], v[236:239], v[100:103]
	v_mfma_f32_16x16x32_bf16 v[96:99], v[142:145], v[236:239], v[96:99]
	v_mfma_f32_16x16x32_bf16 v[124:127], v[138:141], v[198:201], v[124:127]
	v_mfma_f32_16x16x32_bf16 v[120:123], v[146:149], v[198:201], v[120:123]
	v_mfma_f32_16x16x32_bf16 v[116:119], v[138:141], v[224:227], v[116:119]
	v_mfma_f32_16x16x32_bf16 v[112:115], v[146:149], v[224:227], v[112:115]
	v_mfma_f32_16x16x32_bf16 v[108:111], v[138:141], v[232:235], v[108:111]
	v_mfma_f32_16x16x32_bf16 v[104:107], v[146:149], v[232:235], v[104:107]
	v_mfma_f32_16x16x32_bf16 v[100:103], v[138:141], v[240:243], v[100:103]
	v_mfma_f32_16x16x32_bf16 v[96:99], v[146:149], v[240:243], v[96:99]
	s_setprio 0
	s_setprio 1
	v_mfma_f32_16x16x32_bf16 v[92:95], v[150:153], v[194:197], v[92:95]
	v_mfma_f32_16x16x32_bf16 v[88:91], v[174:177], v[194:197], v[88:91]
	v_mfma_f32_16x16x32_bf16 v[84:87], v[150:153], v[202:205], v[84:87]
	v_mfma_f32_16x16x32_bf16 v[80:83], v[174:177], v[202:205], v[80:83]
	v_mfma_f32_16x16x32_bf16 v[76:79], v[150:153], v[228:231], v[76:79]
	v_mfma_f32_16x16x32_bf16 v[72:75], v[174:177], v[228:231], v[72:75]
	v_mfma_f32_16x16x32_bf16 v[68:71], v[150:153], v[236:239], v[68:71]
	v_mfma_f32_16x16x32_bf16 v[64:67], v[174:177], v[236:239], v[64:67]
	v_mfma_f32_16x16x32_bf16 v[92:95], v[154:157], v[198:201], v[92:95]
	v_mfma_f32_16x16x32_bf16 v[88:91], v[190:193], v[198:201], v[88:91]
	v_mfma_f32_16x16x32_bf16 v[84:87], v[154:157], v[224:227], v[84:87]
	v_mfma_f32_16x16x32_bf16 v[80:83], v[190:193], v[224:227], v[80:83]
	v_mfma_f32_16x16x32_bf16 v[76:79], v[154:157], v[232:235], v[76:79]
	v_mfma_f32_16x16x32_bf16 v[72:75], v[190:193], v[232:235], v[72:75]
	v_mfma_f32_16x16x32_bf16 v[68:71], v[154:157], v[240:243], v[68:71]
	v_mfma_f32_16x16x32_bf16 v[64:67], v[190:193], v[240:243], v[64:67]
	s_setprio 0
	s_barrier
; #define PG8_STAGE(bufoff, gbase, voff) do { _Pragma("unroll") for (int _i = 0; _i < 2; ++_i) \
;         __builtin_amdgcn_global_load_lds((const unsigned*)((const char*)(gbase) + (voff)[_i]), (LAS unsigned*)(lds + (bufoff) + ldsw + _i * 8192), 16, 0, 0); } while (0)
; #define PG8_LDA(dst, b, h) do { _Pragma("unroll") for (int m = 0; m < 4; ++m) _Pragma("unroll") for (int k = 0; k < 2; ++k) dst[m][k] = *(const LAS bf16x8*)(lds + PG8_SA(b, h) + aoff + m * 2048 + k * 1024); } while (0)
; #define PG8_MMA(ai, bj, At, Bt) do { __builtin_amdgcn_s_setprio(1); _Pragma("unroll") for (int m = 0; m < 4; ++m) _Pragma("unroll") for (int n = 0; n < 2; ++n) _Pragma("unroll") for (int k = 0; k < 2; ++k) \
;         acc[ai][bj][m][n] = __builtin_amdgcn_mfma_f32_16x16x32_bf16(Bt[n][k], At[m][k], acc[ai][bj][m][n], 0, 0, 0); __builtin_amdgcn_s_setprio(0); } while (0)
; #define PG8_WAIT_V(n) asm volatile("s_waitcnt vmcnt(" #n ")" ::: "memory")
; #define PG8_WAIT_L(n) asm volatile("s_waitcnt lgkmcnt(" #n ")" ::: "memory")
; #define PG8_BAR __builtin_amdgcn_s_barrier()
; #define PG8_SCHED __builtin_amdgcn_sched_barrier(0)
;     ...
;             PG8_LDA(At, 1, 1); PG8_STAGE(PG8_SB(1, 0), b3, voffB); PG8_STAGE(PG8_SB(1, 1), b3 + hstepB, voffB); PG8_STAGE(PG8_SA(1, 0), a3, voffA);
;             PG8_WAIT_V(8); PG8_WAIT_L(0); PG8_BAR; PG8_MMA(1, 0, At, B0); PG8_MMA(1, 1, At, B1); PG8_BAR; PG8_SCHED;
;         }
;         if (wr == 0) PG8_BAR;
	s_nop 0
	s_add_i32 s19, s19, s10
	s_add_i32 m0, s19, 0xffffff80
	ds_read_b128 v[194:197], v188 offset:49152
	ds_read_b128 v[198:201], v188 offset:50176
	ds_read_b128 v[202:205], v188 offset:51200
	ds_read_b128 v[224:227], v188 offset:52224
	ds_read_b128 v[228:231], v188 offset:53248
	ds_read_b128 v[232:235], v188 offset:54272
	ds_read_b128 v[236:239], v188 offset:55296
	ds_read_b128 v[240:243], v188 offset:56320
	global_load_lds_dwordx4 v[178:179], off offset:128
	s_add_i32 m0, s19, 0x1f80
	s_add_i32 s19, s27, s10
	global_load_lds_dwordx4 v[212:213], off offset:128
	s_add_i32 m0, s19, 0xffffff80
	s_nop 0
	global_load_lds_dwordx4 v[218:219], off offset:128
	s_add_i32 m0, s19, 0x1f80
	s_nop 0
	global_load_lds_dwordx4 v[158:159], off offset:128
	s_add_i32 m0, s62, 0xffffff80
	s_nop 0
	global_load_lds_dwordx4 v[244:245], off offset:128
	s_add_i32 m0, s63, 0xffffff80
	s_nop 0
	global_load_lds_dwordx4 v[246:247], off offset:128
	s_waitcnt vmcnt(8)
	s_waitcnt lgkmcnt(0)
	s_barrier
	s_setprio 1
	s_waitcnt lgkmcnt(0)
	v_mfma_f32_16x16x32_bf16 v[60:63], v[134:137], v[194:197], v[60:63]
	v_mfma_f32_16x16x32_bf16 v[56:59], v[142:145], v[194:197], v[56:59]
	v_mfma_f32_16x16x32_bf16 v[52:55], v[134:137], v[202:205], v[52:55]
	v_mfma_f32_16x16x32_bf16 v[48:51], v[142:145], v[202:205], v[48:51]
	v_mfma_f32_16x16x32_bf16 v[44:47], v[134:137], v[228:231], v[44:47]
	v_mfma_f32_16x16x32_bf16 v[40:43], v[142:145], v[228:231], v[40:43]
	v_mfma_f32_16x16x32_bf16 v[36:39], v[134:137], v[236:239], v[36:39]
	v_mfma_f32_16x16x32_bf16 v[32:35], v[142:145], v[236:239], v[32:35]
	v_mfma_f32_16x16x32_bf16 v[60:63], v[138:141], v[198:201], v[60:63]
	v_mfma_f32_16x16x32_bf16 v[56:59], v[146:149], v[198:201], v[56:59]
	v_mfma_f32_16x16x32_bf16 v[52:55], v[138:141], v[224:227], v[52:55]
	v_mfma_f32_16x16x32_bf16 v[48:51], v[146:149], v[224:227], v[48:51]
	v_mfma_f32_16x16x32_bf16 v[44:47], v[138:141], v[232:235], v[44:47]
	v_mfma_f32_16x16x32_bf16 v[40:43], v[146:149], v[232:235], v[40:43]
	v_mfma_f32_16x16x32_bf16 v[36:39], v[138:141], v[240:243], v[36:39]
	v_mfma_f32_16x16x32_bf16 v[32:35], v[146:149], v[240:243], v[32:35]
	s_setprio 0
	s_setprio 1
	v_mfma_f32_16x16x32_bf16 v[28:31], v[150:153], v[194:197], v[28:31]
	v_mfma_f32_16x16x32_bf16 v[24:27], v[174:177], v[194:197], v[24:27]
	v_mfma_f32_16x16x32_bf16 v[20:23], v[150:153], v[202:205], v[20:23]
	v_mfma_f32_16x16x32_bf16 v[16:19], v[174:177], v[202:205], v[16:19]
	v_mfma_f32_16x16x32_bf16 v[12:15], v[150:153], v[228:231], v[12:15]
	v_mfma_f32_16x16x32_bf16 v[8:11], v[174:177], v[228:231], v[8:11]
	v_mfma_f32_16x16x32_bf16 v[4:7], v[150:153], v[236:239], v[4:7]
	v_mfma_f32_16x16x32_bf16 v[0:3], v[174:177], v[236:239], v[0:3]
	v_mfma_f32_16x16x32_bf16 v[28:31], v[154:157], v[198:201], v[28:31]
	v_mfma_f32_16x16x32_bf16 v[24:27], v[190:193], v[198:201], v[24:27]
	v_mfma_f32_16x16x32_bf16 v[20:23], v[154:157], v[224:227], v[20:23]
	v_mfma_f32_16x16x32_bf16 v[16:19], v[190:193], v[224:227], v[16:19]
	v_mfma_f32_16x16x32_bf16 v[12:15], v[154:157], v[232:235], v[12:15]
	v_mfma_f32_16x16x32_bf16 v[8:11], v[190:193], v[232:235], v[8:11]
	v_mfma_f32_16x16x32_bf16 v[4:7], v[154:157], v[240:243], v[4:7]
	v_mfma_f32_16x16x32_bf16 v[0:3], v[190:193], v[240:243], v[0:3]
	s_setprio 0
	s_barrier
	s_add_u32 s0, s0, 0x100
	s_addc_u32 s1, s1, 0
	v_lshl_add_u64 v[130:131], v[130:131], 0, s[94:95]
	v_lshl_add_u64 v[128:129], v[128:129], 0, s[94:95]
	s_cmp_ge_u32 s57, s16
	s_mov_b32 s38, s57
	s_cbranch_scc0 .LBB0_318
	v_readlane_b32 s0, v254, 50
	v_readlane_b32 s1, v254, 51
	s_and_b64 vcc, exec, s[0:1]
	s_mov_b32 s68, 0x134000
	s_mov_b32 s69, 0x160000
	s_cbranch_vccz .LBB0_321
	s_barrier

; #define PG8_STAGE(bufoff, gbase, voff) do { _Pragma("unroll") for (int _i = 0; _i < 2; ++_i) \
;         __builtin_amdgcn_global_load_lds((const unsigned*)((const char*)(gbase) + (voff)[_i]), (LAS unsigned*)(lds + (bufoff) + ldsw + _i * 8192), 16, 0, 0); } while (0)
; #define PG8_LDA(dst, b, h) do { _Pragma("unroll") for (int m = 0; m < 4; ++m) _Pragma("unroll") for (int k = 0; k < 2; ++k) dst[m][k] = *(const LAS bf16x8*)(lds + PG8_SA(b, h) + aoff + m * 2048 + k * 1024); } while (0)
; #define PG8_LDB(dst, b, h) do { _Pragma("unroll") for (int n = 0; n < 2; ++n) _Pragma("unroll") for (int k = 0; k < 2; ++k) dst[n][k] = *(const LAS bf16x8*)(lds + PG8_SB(b, h) + boff + n * 2048 + k * 1024); } while (0)
; #define PG8_MMA(ai, bj, At, Bt) do { __builtin_amdgcn_s_setprio(1); _Pragma("unroll") for (int m = 0; m < 4; ++m) _Pragma("unroll") for (int n = 0; n < 2; ++n) _Pragma("unroll") for (int k = 0; k < 2; ++k) \
;         acc[ai][bj][m][n] = __builtin_amdgcn_mfma_f32_16x16x32_bf16(Bt[n][k], At[m][k], acc[ai][bj][m][n], 0, 0, 0); __builtin_amdgcn_s_setprio(0); } while (0)
; #define PG8_WAIT_V(n) asm volatile("s_waitcnt vmcnt(" #n ")" ::: "memory")
; #define PG8_WAIT_L(n) asm volatile("s_waitcnt lgkmcnt(" #n ")" ::: "memory")
; #define PG8_BAR __builtin_amdgcn_s_barrier()
; #define PG8_SCHED __builtin_amdgcn_sched_barrier(0)
;     ...
;             const bool last = (t == nt - 2);
;             const char* a1 = cA + (size_t)(t + 1) * kstep;
;             const char* a2 = last ? nA : cA + (size_t)(t + 2) * kstep; const char* b2 = last ? nB : cB + (size_t)(t + 2) * kstep;
;             const char* a3 = a2 + kstep; const char* b3 = b2 + kstep;
;             PG8_LDB(B0, 0, 0); PG8_LDB(B1, 0, 1); PG8_SCHED; PG8_LDA(At, 0, 0); PG8_STAGE(PG8_SA(1, 1), a1 + hstepA, voffA);
;             PG8_WAIT_V(8); PG8_WAIT_L(0); PG8_BAR; PG8_MMA(0, 0, At, B0); PG8_MMA(0, 1, At, B1); PG8_BAR; PG8_SCHED;
;             PG8_LDA(At, 0, 1); PG8_STAGE(PG8_SB(0, 0), b2, voffB); PG8_STAGE(PG8_SB(0, 1), b2 + hstepB, voffB); PG8_STAGE(PG8_SA(0, 0), a2, voffA);
;             PG8_WAIT_V(8); PG8_WAIT_L(0); PG8_BAR; PG8_MMA(1, 0, At, B0); PG8_MMA(1, 1, At, B1); PG8_BAR; PG8_SCHED;
.LBB0_416:
	s_add_i32 s8, s2, 2
	s_add_u32 s9, s52, s0
	s_addc_u32 s3, s53, s1
	s_add_i32 s26, 0, 0x10000
	s_cmp_eq_u32 s65, s2
	s_cselect_b32 s3, s6, s3
	s_cselect_b32 s2, s7, s9
	v_add_u32_e32 v153, s26, v148
	s_cselect_b64 vcc, -1, 0
	s_add_i32 s9, 0, 0x14000
	v_lshl_add_u64 v[170:171], v[128:129], 0, s[0:1]
	ds_read_b128 v[154:157], v153
	ds_read_b128 v[158:161], v153 offset:1024
	ds_read_b128 v[162:165], v153 offset:2048
	ds_read_b128 v[166:169], v153 offset:3072
	v_add_u32_e32 v153, s9, v148
	v_cndmask_b32_e32 v205, v171, v151, vcc
	v_cndmask_b32_e32 v204, v170, v152, vcc
	ds_read_b128 v[170:173], v153
	ds_read_b128 v[174:177], v153 offset:1024
	ds_read_b128 v[178:181], v153 offset:2048
	ds_read_b128 v[188:191], v153 offset:3072
	v_lshl_add_u64 v[244:245], s[52:53], 0, v[146:147]
	s_add_i32 m0, s41, 0xc000
	ds_read_b128 v[192:195], v149
	ds_read_b128 v[196:199], v149 offset:1024
	ds_read_b128 v[200:203], v149 offset:2048
	ds_read_b128 v[224:227], v149 offset:3072
	ds_read_b128 v[228:231], v149 offset:4096
	ds_read_b128 v[232:235], v149 offset:5120
	ds_read_b128 v[236:239], v149 offset:6144
	ds_read_b128 v[240:243], v149 offset:7168
	global_load_lds_dwordx4 v[244:245], off
	v_lshl_add_u64 v[244:245], s[52:53], 0, v[144:145]
	s_add_i32 m0, s41, 0xe000
	s_nop 0
	global_load_lds_dwordx4 v[244:245], off
	s_waitcnt vmcnt(8)
	s_waitcnt lgkmcnt(0)
	s_barrier
	s_setprio 1
	s_waitcnt lgkmcnt(0)
	v_mfma_f32_16x16x32_bf16 v[124:127], v[154:157], v[192:195], v[124:127]
	v_mfma_f32_16x16x32_bf16 v[120:123], v[162:165], v[192:195], v[120:123]
	v_mfma_f32_16x16x32_bf16 v[116:119], v[154:157], v[200:203], v[116:119]
	v_mfma_f32_16x16x32_bf16 v[112:115], v[162:165], v[200:203], v[112:115]
	v_mfma_f32_16x16x32_bf16 v[108:111], v[154:157], v[228:231], v[108:111]
	v_mfma_f32_16x16x32_bf16 v[104:107], v[162:165], v[228:231], v[104:107]
	v_mfma_f32_16x16x32_bf16 v[100:103], v[154:157], v[236:239], v[100:103]
	v_mfma_f32_16x16x32_bf16 v[96:99], v[162:165], v[236:239], v[96:99]
	v_mfma_f32_16x16x32_bf16 v[124:127], v[158:161], v[196:199], v[124:127]
	v_mfma_f32_16x16x32_bf16 v[120:123], v[166:169], v[196:199], v[120:123]
	v_mfma_f32_16x16x32_bf16 v[116:119], v[158:161], v[224:227], v[116:119]
	v_mfma_f32_16x16x32_bf16 v[112:115], v[166:169], v[224:227], v[112:115]
	v_mfma_f32_16x16x32_bf16 v[108:111], v[158:161], v[232:235], v[108:111]
	v_mfma_f32_16x16x32_bf16 v[104:107], v[166:169], v[232:235], v[104:107]
	v_mfma_f32_16x16x32_bf16 v[100:103], v[158:161], v[240:243], v[100:103]
	v_mfma_f32_16x16x32_bf16 v[96:99], v[166:169], v[240:243], v[96:99]
	s_setprio 0
	s_setprio 1
	v_mfma_f32_16x16x32_bf16 v[92:95], v[170:173], v[192:195], v[92:95]
	v_mfma_f32_16x16x32_bf16 v[88:91], v[178:181], v[192:195], v[88:91]
	v_mfma_f32_16x16x32_bf16 v[84:87], v[170:173], v[200:203], v[84:87]
	v_mfma_f32_16x16x32_bf16 v[80:83], v[178:181], v[200:203], v[80:83]
	v_mfma_f32_16x16x32_bf16 v[76:79], v[170:173], v[228:231], v[76:79]
	v_mfma_f32_16x16x32_bf16 v[72:75], v[178:181], v[228:231], v[72:75]
	v_mfma_f32_16x16x32_bf16 v[68:71], v[170:173], v[236:239], v[68:71]
	v_mfma_f32_16x16x32_bf16 v[64:67], v[178:181], v[236:239], v[64:67]
	v_mfma_f32_16x16x32_bf16 v[92:95], v[174:177], v[196:199], v[92:95]
	v_mfma_f32_16x16x32_bf16 v[88:91], v[188:191], v[196:199], v[88:91]
	v_mfma_f32_16x16x32_bf16 v[84:87], v[174:177], v[224:227], v[84:87]
	v_mfma_f32_16x16x32_bf16 v[80:83], v[188:191], v[224:227], v[80:83]
	v_mfma_f32_16x16x32_bf16 v[76:79], v[174:177], v[232:235], v[76:79]
	v_mfma_f32_16x16x32_bf16 v[72:75], v[188:191], v[232:235], v[72:75]
	v_mfma_f32_16x16x32_bf16 v[68:71], v[174:177], v[240:243], v[68:71]
	v_mfma_f32_16x16x32_bf16 v[64:67], v[188:191], v[240:243], v[64:67]
	s_setprio 0
	s_barrier
	s_add_i32 s26, s26, s40
	v_lshl_add_u64 v[244:245], v[204:205], 0, v[132:133]
	s_mov_b32 m0, s26
	ds_read_b128 v[192:195], v149 offset:16384
	ds_read_b128 v[196:199], v149 offset:17408
	ds_read_b128 v[200:203], v149 offset:18432
	ds_read_b128 v[224:227], v149 offset:19456
	ds_read_b128 v[228:231], v149 offset:20480
	ds_read_b128 v[232:235], v149 offset:21504
	ds_read_b128 v[236:239], v149 offset:22528
	ds_read_b128 v[240:243], v149 offset:23552
	global_load_lds_dwordx4 v[244:245], off
	v_lshl_add_u64 v[246:247], v[204:205], 0, v[136:137]
	s_add_i32 m0, s26, 0x2000
	v_lshl_add_u64 v[204:205], v[204:205], 0, s[58:59]
	s_add_i32 s9, s9, s40
	global_load_lds_dwordx4 v[246:247], off
	v_lshl_add_u64 v[248:249], v[204:205], 0, v[132:133]
	s_mov_b32 m0, s9
	v_lshl_add_u64 v[204:205], v[204:205], 0, v[136:137]
	global_load_lds_dwordx4 v[248:249], off
	s_add_i32 m0, s9, 0x2000
	v_lshl_add_u64 v[250:251], s[2:3], 0, v[130:131]
	global_load_lds_dwordx4 v[204:205], off
	s_mov_b32 m0, s41
	v_lshl_add_u64 v[218:219], s[2:3], 0, v[134:135]
	global_load_lds_dwordx4 v[250:251], off
	s_mov_b32 m0, s49
	s_nop 0
	global_load_lds_dwordx4 v[218:219], off
	s_waitcnt vmcnt(8)
	s_waitcnt lgkmcnt(0)
	s_barrier
; #define PG8_STAGE(bufoff, gbase, voff) do { _Pragma("unroll") for (int _i = 0; _i < 2; ++_i) \
;         __builtin_amdgcn_global_load_lds((const unsigned*)((const char*)(gbase) + (voff)[_i]), (LAS unsigned*)(lds + (bufoff) + ldsw + _i * 8192), 16, 0, 0); } while (0)
; #define PG8_LDA(dst, b, h) do { _Pragma("unroll") for (int m = 0; m < 4; ++m) _Pragma("unroll") for (int k = 0; k < 2; ++k) dst[m][k] = *(const LAS bf16x8*)(lds + PG8_SA(b, h) + aoff + m * 2048 + k * 1024); } while (0)
; #define PG8_LDB(dst, b, h) do { _Pragma("unroll") for (int n = 0; n < 2; ++n) _Pragma("unroll") for (int k = 0; k < 2; ++k) dst[n][k] = *(const LAS bf16x8*)(lds + PG8_SB(b, h) + boff + n * 2048 + k * 1024); } while (0)
; #define PG8_MMA(ai, bj, At, Bt) do { __builtin_amdgcn_s_setprio(1); _Pragma("unroll") for (int m = 0; m < 4; ++m) _Pragma("unroll") for (int n = 0; n < 2; ++n) _Pragma("unroll") for (int k = 0; k < 2; ++k) \
;         acc[ai][bj][m][n] = __builtin_amdgcn_mfma_f32_16x16x32_bf16(Bt[n][k], At[m][k], acc[ai][bj][m][n], 0, 0, 0); __builtin_amdgcn_s_setprio(0); } while (0)
; #define PG8_WAIT_V(n) asm volatile("s_waitcnt vmcnt(" #n ")" ::: "memory")
; #define PG8_WAIT_L(n) asm volatile("s_waitcnt lgkmcnt(" #n ")" ::: "memory")
; #define PG8_BAR __builtin_amdgcn_s_barrier()
; #define PG8_SCHED __builtin_amdgcn_sched_barrier(0)
;     ...
;             PG8_WAIT_V(8); PG8_WAIT_L(0); PG8_BAR; PG8_MMA(1, 0, At, B0); PG8_MMA(1, 1, At, B1); PG8_BAR; PG8_SCHED;
;             PG8_LDB(B0, 1, 0); PG8_LDB(B1, 1, 1); PG8_SCHED; PG8_LDA(At, 1, 0); PG8_STAGE(PG8_SA(0, 1), a2 + hstepA, voffA);
;             PG8_WAIT_V(8); PG8_WAIT_L(0); PG8_BAR; PG8_MMA(0, 0, At, B0); PG8_MMA(0, 1, At, B1); PG8_BAR; PG8_SCHED;
	s_setprio 1
	s_waitcnt lgkmcnt(0)
	v_mfma_f32_16x16x32_bf16 v[60:63], v[154:157], v[192:195], v[60:63]
	v_mfma_f32_16x16x32_bf16 v[56:59], v[162:165], v[192:195], v[56:59]
	v_mfma_f32_16x16x32_bf16 v[52:55], v[154:157], v[200:203], v[52:55]
	v_mfma_f32_16x16x32_bf16 v[48:51], v[162:165], v[200:203], v[48:51]
	v_mfma_f32_16x16x32_bf16 v[44:47], v[154:157], v[228:231], v[44:47]
	v_mfma_f32_16x16x32_bf16 v[40:43], v[162:165], v[228:231], v[40:43]
	v_mfma_f32_16x16x32_bf16 v[36:39], v[154:157], v[236:239], v[36:39]
	v_mfma_f32_16x16x32_bf16 v[32:35], v[162:165], v[236:239], v[32:35]
	v_mfma_f32_16x16x32_bf16 v[60:63], v[158:161], v[196:199], v[60:63]
	v_mfma_f32_16x16x32_bf16 v[56:59], v[166:169], v[196:199], v[56:59]
	v_mfma_f32_16x16x32_bf16 v[52:55], v[158:161], v[224:227], v[52:55]
	v_mfma_f32_16x16x32_bf16 v[48:51], v[166:169], v[224:227], v[48:51]
	v_mfma_f32_16x16x32_bf16 v[44:47], v[158:161], v[232:235], v[44:47]
	v_mfma_f32_16x16x32_bf16 v[40:43], v[166:169], v[232:235], v[40:43]
	v_mfma_f32_16x16x32_bf16 v[36:39], v[158:161], v[240:243], v[36:39]
	v_mfma_f32_16x16x32_bf16 v[32:35], v[166:169], v[240:243], v[32:35]
	s_setprio 0
	s_setprio 1
	v_mfma_f32_16x16x32_bf16 v[28:31], v[170:173], v[192:195], v[28:31]
	v_mfma_f32_16x16x32_bf16 v[24:27], v[178:181], v[192:195], v[24:27]
	v_mfma_f32_16x16x32_bf16 v[20:23], v[170:173], v[200:203], v[20:23]
	v_mfma_f32_16x16x32_bf16 v[16:19], v[178:181], v[200:203], v[16:19]
	v_mfma_f32_16x16x32_bf16 v[12:15], v[170:173], v[228:231], v[12:15]
	v_mfma_f32_16x16x32_bf16 v[8:11], v[178:181], v[228:231], v[8:11]
	v_mfma_f32_16x16x32_bf16 v[4:7], v[170:173], v[236:239], v[4:7]
	v_mfma_f32_16x16x32_bf16 v[0:3], v[178:181], v[236:239], v[0:3]
	v_mfma_f32_16x16x32_bf16 v[28:31], v[174:177], v[196:199], v[28:31]
	v_mfma_f32_16x16x32_bf16 v[24:27], v[188:191], v[196:199], v[24:27]
	v_mfma_f32_16x16x32_bf16 v[20:23], v[174:177], v[224:227], v[20:23]
	v_mfma_f32_16x16x32_bf16 v[16:19], v[188:191], v[224:227], v[16:19]
	v_mfma_f32_16x16x32_bf16 v[12:15], v[174:177], v[232:235], v[12:15]
	v_mfma_f32_16x16x32_bf16 v[8:11], v[188:191], v[232:235], v[8:11]
	v_mfma_f32_16x16x32_bf16 v[4:7], v[174:177], v[240:243], v[4:7]
	v_mfma_f32_16x16x32_bf16 v[0:3], v[188:191], v[240:243], v[0:3]
	s_setprio 0
	s_barrier
	s_add_i32 s9, 0, 0x18000
	v_add_u32_e32 v153, s9, v148
	s_add_i32 s26, 0, 0x1c000
	ds_read_b128 v[154:157], v153
	ds_read_b128 v[158:161], v153 offset:1024
	ds_read_b128 v[162:165], v153 offset:2048
	ds_read_b128 v[166:169], v153 offset:3072
	v_add_u32_e32 v153, s26, v148
	ds_read_b128 v[170:173], v153
	ds_read_b128 v[174:177], v153 offset:1024
	ds_read_b128 v[178:181], v153 offset:2048
	ds_read_b128 v[188:191], v153 offset:3072
	s_add_u32 s2, s2, s58
	s_addc_u32 s3, s3, 0
	s_mov_b32 m0, s10
	v_lshl_add_u64 v[212:213], s[2:3], 0, v[130:131]
	ds_read_b128 v[192:195], v149 offset:32768
	ds_read_b128 v[196:199], v149 offset:33792
	ds_read_b128 v[200:203], v149 offset:34816
	ds_read_b128 v[224:227], v149 offset:35840
	ds_read_b128 v[228:231], v149 offset:36864
	ds_read_b128 v[232:235], v149 offset:37888
	ds_read_b128 v[236:239], v149 offset:38912
	ds_read_b128 v[240:243], v149 offset:39936
	global_load_lds_dwordx4 v[212:213], off
	v_lshl_add_u64 v[212:213], s[2:3], 0, v[134:135]
	s_mov_b32 m0, s11
	s_nop 0
	global_load_lds_dwordx4 v[212:213], off
	s_waitcnt vmcnt(8)
	s_waitcnt lgkmcnt(0)
	s_barrier
	s_setprio 1
	s_waitcnt lgkmcnt(0)
	v_mfma_f32_16x16x32_bf16 v[124:127], v[154:157], v[192:195], v[124:127]
	v_mfma_f32_16x16x32_bf16 v[120:123], v[162:165], v[192:195], v[120:123]
	v_mfma_f32_16x16x32_bf16 v[116:119], v[154:157], v[200:203], v[116:119]
	v_mfma_f32_16x16x32_bf16 v[112:115], v[162:165], v[200:203], v[112:115]
	v_mfma_f32_16x16x32_bf16 v[108:111], v[154:157], v[228:231], v[108:111]
	v_mfma_f32_16x16x32_bf16 v[104:107], v[162:165], v[228:231], v[104:107]
	v_mfma_f32_16x16x32_bf16 v[100:103], v[154:157], v[236:239], v[100:103]
	v_mfma_f32_16x16x32_bf16 v[96:99], v[162:165], v[236:239], v[96:99]
	v_mfma_f32_16x16x32_bf16 v[124:127], v[158:161], v[196:199], v[124:127]
	v_mfma_f32_16x16x32_bf16 v[120:123], v[166:169], v[196:199], v[120:123]
	v_mfma_f32_16x16x32_bf16 v[116:119], v[158:161], v[224:227], v[116:119]
	v_mfma_f32_16x16x32_bf16 v[112:115], v[166:169], v[224:227], v[112:115]
	v_mfma_f32_16x16x32_bf16 v[108:111], v[158:161], v[232:235], v[108:111]
	v_mfma_f32_16x16x32_bf16 v[104:107], v[166:169], v[232:235], v[104:107]
	v_mfma_f32_16x16x32_bf16 v[100:103], v[158:161], v[240:243], v[100:103]
	v_mfma_f32_16x16x32_bf16 v[96:99], v[166:169], v[240:243], v[96:99]
	s_setprio 0
	s_setprio 1
	v_mfma_f32_16x16x32_bf16 v[92:95], v[170:173], v[192:195], v[92:95]
	v_mfma_f32_16x16x32_bf16 v[88:91], v[178:181], v[192:195], v[88:91]
	v_mfma_f32_16x16x32_bf16 v[84:87], v[170:173], v[200:203], v[84:87]
	v_mfma_f32_16x16x32_bf16 v[80:83], v[178:181], v[200:203], v[80:83]
	v_mfma_f32_16x16x32_bf16 v[76:79], v[170:173], v[228:231], v[76:79]
	v_mfma_f32_16x16x32_bf16 v[72:75], v[178:181], v[228:231], v[72:75]
	v_mfma_f32_16x16x32_bf16 v[68:71], v[170:173], v[236:239], v[68:71]
	v_mfma_f32_16x16x32_bf16 v[64:67], v[178:181], v[236:239], v[64:67]
	v_mfma_f32_16x16x32_bf16 v[92:95], v[174:177], v[196:199], v[92:95]
	v_mfma_f32_16x16x32_bf16 v[88:91], v[188:191], v[196:199], v[88:91]
	v_mfma_f32_16x16x32_bf16 v[84:87], v[174:177], v[224:227], v[84:87]
	v_mfma_f32_16x16x32_bf16 v[80:83], v[188:191], v[224:227], v[80:83]
	v_mfma_f32_16x16x32_bf16 v[76:79], v[174:177], v[232:235], v[76:79]
	v_mfma_f32_16x16x32_bf16 v[72:75], v[188:191], v[232:235], v[72:75]
	v_mfma_f32_16x16x32_bf16 v[68:71], v[174:177], v[240:243], v[68:71]
	v_mfma_f32_16x16x32_bf16 v[64:67], v[188:191], v[240:243], v[64:67]
	s_setprio 0
	s_barrier
; #define PG8_STAGE(bufoff, gbase, voff) do { _Pragma("unroll") for (int _i = 0; _i < 2; ++_i) \
;         __builtin_amdgcn_global_load_lds((const unsigned*)((const char*)(gbase) + (voff)[_i]), (LAS unsigned*)(lds + (bufoff) + ldsw + _i * 8192), 16, 0, 0); } while (0)
; #define PG8_LDA(dst, b, h) do { _Pragma("unroll") for (int m = 0; m < 4; ++m) _Pragma("unroll") for (int k = 0; k < 2; ++k) dst[m][k] = *(const LAS bf16x8*)(lds + PG8_SA(b, h) + aoff + m * 2048 + k * 1024); } while (0)
; #define PG8_MMA(ai, bj, At, Bt) do { __builtin_amdgcn_s_setprio(1); _Pragma("unroll") for (int m = 0; m < 4; ++m) _Pragma("unroll") for (int n = 0; n < 2; ++n) _Pragma("unroll") for (int k = 0; k < 2; ++k) \
;         acc[ai][bj][m][n] = __builtin_amdgcn_mfma_f32_16x16x32_bf16(Bt[n][k], At[m][k], acc[ai][bj][m][n], 0, 0, 0); __builtin_amdgcn_s_setprio(0); } while (0)
; #define PG8_WAIT_V(n) asm volatile("s_waitcnt vmcnt(" #n ")" ::: "memory")
; #define PG8_WAIT_L(n) asm volatile("s_waitcnt lgkmcnt(" #n ")" ::: "memory")
; #define PG8_BAR __builtin_amdgcn_s_barrier()
; #define PG8_SCHED __builtin_amdgcn_sched_barrier(0)
;     ...
;             PG8_LDA(At, 1, 1); PG8_STAGE(PG8_SB(1, 0), b3, voffB); PG8_STAGE(PG8_SB(1, 1), b3 + hstepB, voffB); PG8_STAGE(PG8_SA(1, 0), a3, voffA);
;             PG8_WAIT_V(8); PG8_WAIT_L(0); PG8_BAR; PG8_MMA(1, 0, At, B0); PG8_MMA(1, 1, At, B1); PG8_BAR; PG8_SCHED;
;         }
;         if (wr == 0) PG8_BAR;
	s_nop 0
	s_add_i32 s2, s9, s40
	s_add_i32 m0, s2, 0xffffff80
	ds_read_b128 v[192:195], v149 offset:49152
	ds_read_b128 v[196:199], v149 offset:50176
	ds_read_b128 v[200:203], v149 offset:51200
	ds_read_b128 v[224:227], v149 offset:52224
	ds_read_b128 v[228:231], v149 offset:53248
	ds_read_b128 v[232:235], v149 offset:54272
	ds_read_b128 v[236:239], v149 offset:55296
	ds_read_b128 v[240:243], v149 offset:56320
	global_load_lds_dwordx4 v[244:245], off offset:128
	s_add_i32 m0, s2, 0x1f80
	s_add_i32 s2, s26, s40
	global_load_lds_dwordx4 v[246:247], off offset:128
	s_add_i32 m0, s2, 0xffffff80
	s_nop 0
	global_load_lds_dwordx4 v[248:249], off offset:128
	s_add_i32 m0, s2, 0x1f80
	s_nop 0
	global_load_lds_dwordx4 v[204:205], off offset:128
	s_add_i32 m0, s51, 0xffffff80
	s_nop 0
	global_load_lds_dwordx4 v[250:251], off offset:128
	s_add_i32 m0, s64, 0xffffff80
	s_nop 0
	global_load_lds_dwordx4 v[218:219], off offset:128
	s_waitcnt vmcnt(8)
	s_waitcnt lgkmcnt(0)
	s_barrier
	s_setprio 1
	s_waitcnt lgkmcnt(0)
	v_mfma_f32_16x16x32_bf16 v[60:63], v[154:157], v[192:195], v[60:63]
	v_mfma_f32_16x16x32_bf16 v[56:59], v[162:165], v[192:195], v[56:59]
	v_mfma_f32_16x16x32_bf16 v[52:55], v[154:157], v[200:203], v[52:55]
	v_mfma_f32_16x16x32_bf16 v[48:51], v[162:165], v[200:203], v[48:51]
	v_mfma_f32_16x16x32_bf16 v[44:47], v[154:157], v[228:231], v[44:47]
	v_mfma_f32_16x16x32_bf16 v[40:43], v[162:165], v[228:231], v[40:43]
	v_mfma_f32_16x16x32_bf16 v[36:39], v[154:157], v[236:239], v[36:39]
	v_mfma_f32_16x16x32_bf16 v[32:35], v[162:165], v[236:239], v[32:35]
	v_mfma_f32_16x16x32_bf16 v[60:63], v[158:161], v[196:199], v[60:63]
	v_mfma_f32_16x16x32_bf16 v[56:59], v[166:169], v[196:199], v[56:59]
	v_mfma_f32_16x16x32_bf16 v[52:55], v[158:161], v[224:227], v[52:55]
	v_mfma_f32_16x16x32_bf16 v[48:51], v[166:169], v[224:227], v[48:51]
	v_mfma_f32_16x16x32_bf16 v[44:47], v[158:161], v[232:235], v[44:47]
	v_mfma_f32_16x16x32_bf16 v[40:43], v[166:169], v[232:235], v[40:43]
	v_mfma_f32_16x16x32_bf16 v[36:39], v[158:161], v[240:243], v[36:39]
	v_mfma_f32_16x16x32_bf16 v[32:35], v[166:169], v[240:243], v[32:35]
	s_setprio 0
	s_setprio 1
	v_mfma_f32_16x16x32_bf16 v[28:31], v[170:173], v[192:195], v[28:31]
	v_mfma_f32_16x16x32_bf16 v[24:27], v[178:181], v[192:195], v[24:27]
	v_mfma_f32_16x16x32_bf16 v[20:23], v[170:173], v[200:203], v[20:23]
	v_mfma_f32_16x16x32_bf16 v[16:19], v[178:181], v[200:203], v[16:19]
	v_mfma_f32_16x16x32_bf16 v[12:15], v[170:173], v[228:231], v[12:15]
	v_mfma_f32_16x16x32_bf16 v[8:11], v[178:181], v[228:231], v[8:11]
	v_mfma_f32_16x16x32_bf16 v[4:7], v[170:173], v[236:239], v[4:7]
	v_mfma_f32_16x16x32_bf16 v[0:3], v[178:181], v[236:239], v[0:3]
	v_mfma_f32_16x16x32_bf16 v[28:31], v[174:177], v[196:199], v[28:31]
	v_mfma_f32_16x16x32_bf16 v[24:27], v[188:191], v[196:199], v[24:27]
	v_mfma_f32_16x16x32_bf16 v[20:23], v[174:177], v[224:227], v[20:23]
	v_mfma_f32_16x16x32_bf16 v[16:19], v[188:191], v[224:227], v[16:19]
	v_mfma_f32_16x16x32_bf16 v[12:15], v[174:177], v[232:235], v[12:15]
	v_mfma_f32_16x16x32_bf16 v[8:11], v[188:191], v[232:235], v[8:11]
	v_mfma_f32_16x16x32_bf16 v[4:7], v[174:177], v[240:243], v[4:7]
	v_mfma_f32_16x16x32_bf16 v[0:3], v[188:191], v[240:243], v[0:3]
	s_setprio 0
	s_barrier
	s_add_u32 s0, s0, 0x100
	s_addc_u32 s1, s1, 0
	v_lshl_add_u64 v[146:147], v[146:147], 0, s[94:95]
	v_lshl_add_u64 v[144:145], v[144:145], 0, s[94:95]
	s_cmp_ge_u32 s8, s48
	s_mov_b32 s2, s8
	s_cbranch_scc0 .LBB0_416
	v_readlane_b32 s0, v254, 45
	v_readlane_b32 s1, v254, 46
	s_and_b64 vcc, exec, s[0:1]
	s_cbranch_vccz .LBB0_419
	s_barrier
